# attention units: waves 4-7 delayed ~640 cycles after the store_kv barrier (stagger) so one SIMD partner's softmax VALU overlaps the other's MFMAs
# baseline (speedup 1.0000x reference)
; #define LAS __attribute__((address_space(3)))
; __device__ __forceinline__ void load_q(bf16x8 (&qr)[4], const UD& x, const unsigned char* ws, int wid, int r32, int hi) {
;     int d, L, cls, t0, sbase; wave_geo(x, wid, d, L, cls, t0, sbase);
;     const bf16_t* Qb = (const bf16_t*)(ws + off_q(x.b));
;     const size_t qtok = (size_t)x.b * SEQ + (size_t)(t0 + r32) * d + cls;
; #pragma unroll
;     for (int d0 = 0; d0 < 4; ++d0) qr[d0] = *(const bf16x8*)(Qb + qtok * AW + x.h * HD + d0 * 16 + hi * 8);
; }
; __device__ __forceinline__ void compute_a(LAS unsigned char* lds, const UD& x, const bf16x8 (&qr)[4], int wid, int lane, u32x4 (&pw)[10], float& mx_o, float& l_o) {
;     const int r32 = lane & 31, hi = lane >> 5;
;     int d, L, cls, t0, sbase; wave_geo(x, wid, d, L, cls, t0, sbase);
;     f32x16 s[5];
; #pragma unroll
;     for (int ht = 0; ht < 5; ++ht) {
;         const LAS unsigned char* kb = lds + L_K + hi * KCS + (sbase + 32 * ht + r32) * 16;
;         f32x16 a = {};
; #pragma unroll
;         for (int d0 = 0; d0 < 4; ++d0) { const bf16x8 kf = *(const LAS bf16x8*)(kb + d0 * 2 * KCS); a = __builtin_amdgcn_mfma_f32_32x32x16_bf16(kf, qr[d0], a, 0, 0, 0); }
;         s[ht] = a;
;     }
;     {
;         const int dq = r32 - 4 * hi;
; #pragma unroll
;         for (int r = 0; r < 16; ++r) { const int cr = (r & 3) + 8 * (r >> 2); s[0][r] = (cr >= dq) ? s[0][r] : -INFINITY; s[4][r] = (cr <= dq) ? s[4][r] : -INFINITY; }
;         if (t0 < 64) {
; template <int MODE> __device__ __forceinline__ void phase(LAS unsigned char* lds, unsigned char* ws, unsigned char* dout, int first, int step, int limit) {
;     ...
;         bf16x8 qr[4]; load_q(qr, x, ws, wid, lane & 31, lane >> 5);
;         store_kv(lds, val, tid);
;         __syncthreads();
.LBB0_634:
	s_ashr_i32 s1, s18, 4
	s_mul_hi_i32 s0, s1, 0x2aaaaaab
	s_lshr_b32 s4, s0, 31
	s_ashr_i32 s0, s0, 1
	s_add_i32 s0, s0, s4
	s_mul_i32 s4, s0, 12
	s_bfe_u32 s13, s18, 0x10003
	s_sub_i32 s20, s1, s4
	s_cmp_eq_u32 s13, 0
	s_cselect_b64 s[22:23], -1, 0
	s_and_b64 s[16:17], s[22:23], exec
	s_cselect_b32 s11, 2, 4
	s_cselect_b32 s21, s45, s9
	s_cselect_b32 s12, s10, s8
	s_ashr_i32 s1, s0, 31
	s_lshl_b64 s[16:17], s[0:1], 23
	v_readlane_b32 s4, v252, 1
	v_cndmask_b32_e64 v0, v214, v194, s[22:23]
	v_readlane_b32 s5, v252, 2
	s_add_u32 s16, s4, s16
	v_or_b32_e32 v2, s12, v160
	s_addc_u32 s17, s5, s17
	s_lshl_b64 s[46:47], s[0:1], 11
	v_ashrrev_i32_e32 v3, 31, v2
	v_ashrrev_i32_e32 v1, 31, v0
	v_lshlrev_b64 v[2:3], s11, v[2:3]
	v_lshl_add_u64 v[150:151], s[46:47], 0, v[0:1]
	v_lshl_add_u64 v[152:153], v[150:151], 0, v[2:3]
	v_mov_b64_e32 v[0:1], s[16:17]
	v_mad_u64_u32 v[0:1], s[16:17], v152, s40, v[0:1]
	s_lshl_b32 s16, s20, 6
	v_mad_i32_i24 v1, v153, s40, v1
	s_ashr_i32 s17, s16, 31
	v_lshl_add_u64 v[0:1], s[16:17], 1, v[0:1]
	v_mov_b32_e32 v147, v81
	v_lshl_add_u64 v[0:1], v[0:1], 0, v[146:147]
	s_mov_b64 s[4:5], 0xc000000
	s_brev_b32 s1, 48
	v_lshl_add_u64 v[2:3], v[0:1], 0, s[4:5]
	v_add_co_u32_e32 v0, vcc, s1, v0
	s_cmp_gt_i32 s12, 63
	s_nop 0
	v_addc_co_u32_e32 v1, vcc, 0, v1, vcc
	global_load_dwordx4 v[48:51], v[0:1], off
	global_load_dwordx4 v[234:237], v[2:3], off offset:32
	global_load_dwordx4 v[242:245], v[2:3], off offset:64
	global_load_dwordx4 v[132:135], v[2:3], off offset:96
	v_or_b32_e32 v0, s21, v160
	v_lshl_add_u32 v80, v0, 4, v161
	s_waitcnt vmcnt(12)
	ds_write_b128 v215, v[84:87]
	ds_write_b128 v216, v[88:91]
	ds_write_b128 v217, v[92:95]
	ds_write_b128 v218, v[96:99]
	ds_write_b128 v219, v[100:103]
	ds_write_b128 v220, v[104:107]
	ds_write_b128 v221, v[108:111]
	ds_write_b128 v222, v[112:115]
	s_waitcnt vmcnt(11)
	ds_write_b128 v223, v[116:119]
	s_waitcnt vmcnt(10)
	ds_write_b128 v224, v[120:123]
	s_waitcnt vmcnt(5)
	ds_write_b128 v225, v[124:127]
	s_waitcnt vmcnt(4)
	ds_write_b128 v226, v[128:131]
	ds_write_b128 v227, v[238:241]
	ds_write_b128 v228, v[238:241]
	s_waitcnt lgkmcnt(0)
	s_barrier
	s_cselect_b32 s99, 1, 0
	v_readfirstlane_b32 s98, v190
	s_bitcmp1_b32 s98, 8
	s_cbranch_scc0 .Lstag_a1
	s_sleep 10
.Lstag_a1:
	s_cmp_lg_u32 s99, 0
	ds_read_b128 v[84:87], v80
	ds_read_b128 v[88:91], v80 offset:14368
	ds_read_b128 v[92:95], v80 offset:28736
	ds_read_b128 v[96:99], v80 offset:43104
	s_waitcnt vmcnt(3) lgkmcnt(3)
	v_mfma_f32_32x32x16_bf16 v[64:79], v[84:87], v[48:51], 0
	ds_read_b128 v[84:87], v80 offset:512
	s_waitcnt vmcnt(2) lgkmcnt(3)
	v_mfma_f32_32x32x16_bf16 v[64:79], v[88:91], v[234:237], v[64:79]
	ds_read_b128 v[88:91], v80 offset:14880
	s_waitcnt vmcnt(1) lgkmcnt(3)
	v_mfma_f32_32x32x16_bf16 v[64:79], v[92:95], v[242:245], v[64:79]
	ds_read_b128 v[92:95], v80 offset:29248
	s_waitcnt vmcnt(0) lgkmcnt(3)
	v_mfma_f32_32x32x16_bf16 v[64:79], v[96:99], v[132:135], v[64:79]
	ds_read_b128 v[96:99], v80 offset:43616
	s_waitcnt lgkmcnt(3)
	v_mfma_f32_32x32x16_bf16 v[32:47], v[84:87], v[48:51], 0
	ds_read_b128 v[84:87], v80 offset:1024
	s_waitcnt lgkmcnt(3)
	v_mfma_f32_32x32x16_bf16 v[32:47], v[88:91], v[234:237], v[32:47]
	ds_read_b128 v[88:91], v80 offset:15392
	s_waitcnt lgkmcnt(3)
	v_mfma_f32_32x32x16_bf16 v[32:47], v[92:95], v[242:245], v[32:47]
	ds_read_b128 v[92:95], v80 offset:29760
	s_waitcnt lgkmcnt(3)
	v_mfma_f32_32x32x16_bf16 v[32:47], v[96:99], v[132:135], v[32:47]
	ds_read_b128 v[96:99], v80 offset:44128
	s_waitcnt lgkmcnt(3)
	v_mfma_f32_32x32x16_bf16 v[16:31], v[84:87], v[48:51], 0
	ds_read_b128 v[84:87], v80 offset:1536
	s_waitcnt lgkmcnt(3)
	v_mfma_f32_32x32x16_bf16 v[16:31], v[88:91], v[234:237], v[16:31]
	ds_read_b128 v[88:91], v80 offset:15904
	s_waitcnt lgkmcnt(3)
	v_mfma_f32_32x32x16_bf16 v[16:31], v[92:95], v[242:245], v[16:31]
	ds_read_b128 v[92:95], v80 offset:30272
	s_waitcnt lgkmcnt(3)
	v_mfma_f32_32x32x16_bf16 v[16:31], v[96:99], v[132:135], v[16:31]
	ds_read_b128 v[96:99], v80 offset:44640
	s_waitcnt lgkmcnt(3)
	v_mfma_f32_32x32x16_bf16 v[0:15], v[84:87], v[48:51], 0
	ds_read_b128 v[84:87], v80 offset:2048
	s_waitcnt lgkmcnt(3)
	v_mfma_f32_32x32x16_bf16 v[0:15], v[88:91], v[234:237], v[0:15]
	ds_read_b128 v[88:91], v80 offset:16416
	s_waitcnt lgkmcnt(3)
	v_mfma_f32_32x32x16_bf16 v[0:15], v[92:95], v[242:245], v[0:15]
	ds_read_b128 v[92:95], v80 offset:30784
	s_waitcnt lgkmcnt(3)
	v_mfma_f32_32x32x16_bf16 v[0:15], v[96:99], v[132:135], v[0:15]
	ds_read_b128 v[96:99], v80 offset:45152
	s_waitcnt lgkmcnt(3)
	v_mfma_f32_32x32x16_bf16 v[48:63], v[84:87], v[48:51], 0
	s_waitcnt lgkmcnt(2)
	v_mfma_f32_32x32x16_bf16 v[48:63], v[88:91], v[234:237], v[48:63]
	s_waitcnt lgkmcnt(1)
	v_mfma_f32_32x32x16_bf16 v[48:63], v[92:95], v[242:245], v[48:63]
	s_waitcnt lgkmcnt(0)
	v_mfma_f32_32x32x16_bf16 v[48:63], v[96:99], v[132:135], v[48:63]
	s_cbranch_scc1 .LBB0_638
	s_cmp_gt_i32 s12, 31
	s_cbranch_scc1 .LBB0_637
	v_mov_b32_e32 v47, 0xff800000
	v_mov_b32_e32 v46, v47
	v_mov_b32_e32 v45, v47
	v_mov_b32_e32 v44, v47
	v_mov_b32_e32 v43, v47
	v_mov_b32_e32 v42, v47
	v_mov_b32_e32 v41, v47
	v_mov_b32_e32 v40, v47
	v_mov_b32_e32 v39, v47
	v_mov_b32_e32 v38, v47
	v_mov_b32_e32 v37, v47
	v_mov_b32_e32 v36, v47
	v_mov_b32_e32 v35, v47
	v_mov_b32_e32 v34, v47
	v_mov_b32_e32 v33, v47
	v_mov_b32_e32 v32, v47

; #define LAS __attribute__((address_space(3)))
; __device__ __forceinline__ void load_q(bf16x8 (&qr)[4], const UD& x, const unsigned char* ws, int wid, int r32, int hi) {
;     int d, L, cls, t0, sbase; wave_geo(x, wid, d, L, cls, t0, sbase);
;     const bf16_t* Qb = (const bf16_t*)(ws + off_q(x.b));
;     const size_t qtok = (size_t)x.b * SEQ + (size_t)(t0 + r32) * d + cls;
; #pragma unroll
;     for (int d0 = 0; d0 < 4; ++d0) qr[d0] = *(const bf16x8*)(Qb + qtok * AW + x.h * HD + d0 * 16 + hi * 8);
; }
; __device__ __forceinline__ void compute_a(LAS unsigned char* lds, const UD& x, const bf16x8 (&qr)[4], int wid, int lane, u32x4 (&pw)[10], float& mx_o, float& l_o) {
;     const int r32 = lane & 31, hi = lane >> 5;
;     int d, L, cls, t0, sbase; wave_geo(x, wid, d, L, cls, t0, sbase);
;     f32x16 s[5];
; #pragma unroll
;     for (int ht = 0; ht < 5; ++ht) {
;         const LAS unsigned char* kb = lds + L_K + hi * KCS + (sbase + 32 * ht + r32) * 16;
;         f32x16 a = {};
; #pragma unroll
;         for (int d0 = 0; d0 < 4; ++d0) { const bf16x8 kf = *(const LAS bf16x8*)(kb + d0 * 2 * KCS); a = __builtin_amdgcn_mfma_f32_32x32x16_bf16(kf, qr[d0], a, 0, 0, 0); }
;         s[ht] = a;
;     }
;     {
;         const int dq = r32 - 4 * hi;
; #pragma unroll
;         for (int r = 0; r < 16; ++r) { const int cr = (r & 3) + 8 * (r >> 2); s[0][r] = (cr >= dq) ? s[0][r] : -INFINITY; s[4][r] = (cr <= dq) ? s[4][r] : -INFINITY; }
;         if (t0 < 64) {
; template <int MODE> __device__ __forceinline__ void phase(LAS unsigned char* lds, unsigned char* ws, unsigned char* dout, int first, int step, int limit) {
;     ...
;         bf16x8 qr[4]; load_q(qr, x, ws, wid, lane & 31, lane >> 5);
;         store_kv(lds, val, tid);
;         __syncthreads();
.LBB0_903:
	s_ashr_i32 s1, s18, 3
	s_mul_hi_i32 s0, s1, 0x2aaaaaab
	s_lshr_b32 s14, s0, 31
	s_ashr_i32 s0, s0, 1
	s_add_i32 s0, s0, s14
	s_mul_i32 s14, s0, 12
	s_sub_i32 s22, s1, s14
	s_lshl_b32 s1, s18, 8
	s_and_b32 s21, s1, 0x700
	s_ashr_i32 s1, s0, 31
	s_lshl_b64 s[14:15], s[0:1], 23
	v_readlane_b32 s16, v252, 1
	v_readlane_b32 s17, v252, 2
	s_add_u32 s16, s16, s14
	v_add_u32_e32 v0, s21, v150
	s_addc_u32 s17, s17, s15
	s_lshl_b64 s[14:15], s[0:1], 11
	v_ashrrev_i32_e32 v1, 31, v0
	v_lshl_add_u64 v[0:1], s[14:15], 0, v[0:1]
	v_mov_b64_e32 v[2:3], s[16:17]
	v_mad_u64_u32 v[2:3], s[16:17], v0, s40, v[2:3]
	s_lshl_b32 s16, s22, 6
	v_mad_i32_i24 v3, v1, s40, v3
	s_ashr_i32 s17, s16, 31
	v_lshl_add_u64 v[0:1], s[16:17], 1, v[2:3]
	v_mov_b32_e32 v143, v81
	v_lshl_add_u64 v[0:1], v[0:1], 0, v[142:143]
	s_mov_b64 s[24:25], 0xc000000
	s_brev_b32 s19, 48
	v_lshl_add_u64 v[2:3], v[0:1], 0, s[24:25]
	v_add_co_u32_e32 v0, vcc, s19, v0
	s_add_i32 s20, s21, s80
	s_nop 0
	v_addc_co_u32_e32 v1, vcc, 0, v1, vcc
	global_load_dwordx4 v[48:51], v[0:1], off
	global_load_dwordx4 v[232:235], v[2:3], off offset:32
	global_load_dwordx4 v[242:245], v[2:3], off offset:64
	global_load_dwordx4 v[246:249], v[2:3], off offset:96
	s_waitcnt vmcnt(4)
	ds_write_b128 v214, v[84:87]
	ds_write_b128 v215, v[88:91]
	ds_write_b128 v216, v[92:95]
	ds_write_b128 v217, v[96:99]
	ds_write_b128 v218, v[100:103]
	ds_write_b128 v219, v[104:107]
	ds_write_b128 v220, v[108:111]
	ds_write_b128 v221, v[112:115]
	ds_write_b128 v222, v[116:119]
	ds_write_b128 v223, v[120:123]
	ds_write_b128 v224, v[124:127]
	ds_write_b128 v225, v[128:131]
	ds_write_b128 v226, v[238:241]
	ds_write_b128 v227, v[238:241]
	s_waitcnt lgkmcnt(0)
	s_barrier
	s_cselect_b32 s99, 1, 0
	v_readfirstlane_b32 s98, v190
	s_bitcmp1_b32 s98, 8
	s_cbranch_scc0 .Lstag_a2
	s_sleep 10
.Lstag_a2:
	s_cmp_lg_u32 s99, 0
	ds_read_b128 v[84:87], v228
	ds_read_b128 v[88:91], v228 offset:14368
	ds_read_b128 v[92:95], v228 offset:28736
	ds_read_b128 v[96:99], v228 offset:43104
	s_cmp_gt_i32 s20, 63
	s_waitcnt vmcnt(3) lgkmcnt(3)
	v_mfma_f32_32x32x16_bf16 v[64:79], v[84:87], v[48:51], 0
	ds_read_b128 v[84:87], v228 offset:512
	s_waitcnt vmcnt(2) lgkmcnt(3)
	v_mfma_f32_32x32x16_bf16 v[64:79], v[88:91], v[232:235], v[64:79]
	ds_read_b128 v[88:91], v228 offset:14880
	s_waitcnt vmcnt(1) lgkmcnt(3)
	v_mfma_f32_32x32x16_bf16 v[64:79], v[92:95], v[242:245], v[64:79]
	ds_read_b128 v[92:95], v228 offset:29248
	s_waitcnt vmcnt(0) lgkmcnt(3)
	v_mfma_f32_32x32x16_bf16 v[64:79], v[96:99], v[246:249], v[64:79]
	ds_read_b128 v[96:99], v228 offset:43616
	s_waitcnt lgkmcnt(3)
	v_mfma_f32_32x32x16_bf16 v[32:47], v[84:87], v[48:51], 0
	ds_read_b128 v[84:87], v228 offset:1024
	s_waitcnt lgkmcnt(3)
	v_mfma_f32_32x32x16_bf16 v[32:47], v[88:91], v[232:235], v[32:47]
	ds_read_b128 v[88:91], v228 offset:15392
	s_waitcnt lgkmcnt(3)
	v_mfma_f32_32x32x16_bf16 v[32:47], v[92:95], v[242:245], v[32:47]
	ds_read_b128 v[92:95], v228 offset:29760
	s_waitcnt lgkmcnt(3)
	v_mfma_f32_32x32x16_bf16 v[32:47], v[96:99], v[246:249], v[32:47]
	ds_read_b128 v[96:99], v228 offset:44128
	s_waitcnt lgkmcnt(3)
	v_mfma_f32_32x32x16_bf16 v[16:31], v[84:87], v[48:51], 0
	ds_read_b128 v[84:87], v228 offset:1536
	s_waitcnt lgkmcnt(3)
	v_mfma_f32_32x32x16_bf16 v[16:31], v[88:91], v[232:235], v[16:31]
	ds_read_b128 v[88:91], v228 offset:15904
	s_waitcnt lgkmcnt(3)
	v_mfma_f32_32x32x16_bf16 v[16:31], v[92:95], v[242:245], v[16:31]
	ds_read_b128 v[92:95], v228 offset:30272
	s_waitcnt lgkmcnt(3)
	v_mfma_f32_32x32x16_bf16 v[16:31], v[96:99], v[246:249], v[16:31]
	ds_read_b128 v[96:99], v228 offset:44640
	s_waitcnt lgkmcnt(3)
	v_mfma_f32_32x32x16_bf16 v[0:15], v[84:87], v[48:51], 0
	ds_read_b128 v[84:87], v228 offset:2048
	s_waitcnt lgkmcnt(3)
	v_mfma_f32_32x32x16_bf16 v[0:15], v[88:91], v[232:235], v[0:15]
	ds_read_b128 v[88:91], v228 offset:16416
	s_waitcnt lgkmcnt(3)
	v_mfma_f32_32x32x16_bf16 v[0:15], v[92:95], v[242:245], v[0:15]
	ds_read_b128 v[92:95], v228 offset:30784
	s_waitcnt lgkmcnt(3)
	v_mfma_f32_32x32x16_bf16 v[0:15], v[96:99], v[246:249], v[0:15]
	ds_read_b128 v[96:99], v228 offset:45152
	s_waitcnt lgkmcnt(3)
	v_mfma_f32_32x32x16_bf16 v[48:63], v[84:87], v[48:51], 0
	s_waitcnt lgkmcnt(2)
	v_mfma_f32_32x32x16_bf16 v[48:63], v[88:91], v[232:235], v[48:63]
	s_waitcnt lgkmcnt(1)
	v_mfma_f32_32x32x16_bf16 v[48:63], v[92:95], v[242:245], v[48:63]
	s_waitcnt lgkmcnt(0)
	v_mfma_f32_32x32x16_bf16 v[48:63], v[96:99], v[246:249], v[48:63]
	s_cbranch_scc1 .LBB0_908
	s_cmp_gt_i32 s20, 31
	s_cbranch_scc1 .LBB0_906
	v_mov_b32_e32 v47, 0xff800000
	v_mov_b32_e32 v46, v47
	v_mov_b32_e32 v45, v47
	v_mov_b32_e32 v44, v47
	v_mov_b32_e32 v43, v47
	v_mov_b32_e32 v42, v47
	v_mov_b32_e32 v41, v47
	v_mov_b32_e32 v40, v47
	v_mov_b32_e32 v39, v47
	v_mov_b32_e32 v38, v47
	v_mov_b32_e32 v37, v47
	v_mov_b32_e32 v36, v47
	v_mov_b32_e32 v35, v47
	v_mov_b32_e32 v34, v47
	v_mov_b32_e32 v33, v47
	v_mov_b32_e32 v32, v47
